# combined: scalar-base LDS-DMA in loops and peeled iterations, stage bases in ds_read offsets, fused loop's running offsets 32-bit (no 64-bit VALU left in any K-loop)
# baseline (speedup 1.0000x reference)
.LBB0_287:
	s_ashr_i32 s21, s20, 31
	s_lshl_b64 s[22:23], s[20:21], 19
	s_add_u32 s22, s80, s22
	s_addc_u32 s23, s81, s23
	s_and_b64 s[24:25], s[6:7], exec
	s_cselect_b32 s21, s23, s29
	s_cselect_b32 s36, s22, s28
	s_ashr_i32 s19, s18, 31
	s_lshl_b64 s[24:25], s[18:19], 19
	s_add_u32 s24, s40, s24
	s_addc_u32 s25, s41, s25
	s_and_b64 s[34:35], s[6:7], exec
	s_cselect_b32 s19, s25, s31
	s_cselect_b32 s37, s24, s30
	s_add_u32 s38, s30, 0x100
	s_addc_u32 s39, s31, 0
	s_add_u32 s28, s28, 0x40080
	s_addc_u32 s29, s29, 0
	s_mov_b32 s55, -2
	s_add_u32 s30, s28, 0xfffc0080
	s_addc_u32 s31, s29, -1
	s_add_i32 s56, 0, 0x10000
	s_cmp_eq_u32 s55, 12
	s_cselect_b32 s35, s21, s31
	s_cselect_b32 s34, s36, s30
	s_cselect_b32 s31, s19, s39
	s_cselect_b32 s30, s37, s38
	s_add_i32 s58, 0, 0x14000
	ds_read_b128 v[142:145], v147
	ds_read_b128 v[158:161], v147 offset:1024
	ds_read_b128 v[162:165], v147 offset:2048
	ds_read_b128 v[166:169], v147 offset:3072
	ds_read_b128 v[170:173], v147 offset:16384
	ds_read_b128 v[174:177], v147 offset:17408
	ds_read_b128 v[178:181], v147 offset:18432
	ds_read_b128 v[182:185], v147 offset:19456
	s_add_i32 m0, s44, 0xc000
	ds_read_b128 v[186:189], v157
	ds_read_b128 v[190:193], v157 offset:1024
	ds_read_b128 v[194:197], v157 offset:2048
	ds_read_b128 v[198:201], v157 offset:3072
	ds_read_b128 v[202:205], v157 offset:4096
	ds_read_b128 v[206:209], v157 offset:5120
	ds_read_b128 v[220:223], v157 offset:6144
	ds_read_b128 v[236:239], v157 offset:7168
	global_load_lds_dwordx4 v140, s[28:29]
	s_add_i32 m0, s44, 0xe000
	s_nop 0
	global_load_lds_dwordx4 v138, s[28:29]
	s_branch .Lpadj_0
	s_nop 0
	s_nop 0
	s_nop 0
	s_nop 0
	s_nop 0
	s_nop 0
	s_nop 0
	s_nop 0

.Lpadj_1:
	s_waitcnt vmcnt(8)
	s_waitcnt lgkmcnt(0)
	s_barrier
	v_mfma_f32_16x16x32_bf16 v[62:65], v[142:145], v[186:189], 0
	v_mfma_f32_16x16x32_bf16 v[58:61], v[162:165], v[186:189], 0
	v_mfma_f32_16x16x32_bf16 v[46:49], v[142:145], v[194:197], 0
	v_mfma_f32_16x16x32_bf16 v[42:45], v[162:165], v[194:197], 0
	v_mfma_f32_16x16x32_bf16 v[30:33], v[142:145], v[202:205], 0
	v_mfma_f32_16x16x32_bf16 v[26:29], v[162:165], v[202:205], 0
	v_mfma_f32_16x16x32_bf16 v[14:17], v[142:145], v[220:223], 0
	v_mfma_f32_16x16x32_bf16 v[10:13], v[162:165], v[220:223], 0
	v_mfma_f32_16x16x32_bf16 v[62:65], v[158:161], v[190:193], v[62:65]
	v_mfma_f32_16x16x32_bf16 v[58:61], v[166:169], v[190:193], v[58:61]
	v_mfma_f32_16x16x32_bf16 v[46:49], v[158:161], v[198:201], v[46:49]
	v_mfma_f32_16x16x32_bf16 v[42:45], v[166:169], v[198:201], v[42:45]
	v_mfma_f32_16x16x32_bf16 v[30:33], v[158:161], v[206:209], v[30:33]
	v_mfma_f32_16x16x32_bf16 v[26:29], v[166:169], v[206:209], v[26:29]
	v_mfma_f32_16x16x32_bf16 v[14:17], v[158:161], v[236:239], v[14:17]
	v_mfma_f32_16x16x32_bf16 v[10:13], v[166:169], v[236:239], v[10:13]
	v_mfma_f32_16x16x32_bf16 v[54:57], v[170:173], v[186:189], 0
	v_mfma_f32_16x16x32_bf16 v[50:53], v[178:181], v[186:189], 0
	v_mfma_f32_16x16x32_bf16 v[38:41], v[170:173], v[194:197], 0
	v_mfma_f32_16x16x32_bf16 v[34:37], v[178:181], v[194:197], 0
	v_mfma_f32_16x16x32_bf16 v[22:25], v[170:173], v[202:205], 0
	v_mfma_f32_16x16x32_bf16 v[18:21], v[178:181], v[202:205], 0
	v_mfma_f32_16x16x32_bf16 v[6:9], v[170:173], v[220:223], 0
	v_mfma_f32_16x16x32_bf16 v[2:5], v[178:181], v[220:223], 0
	v_mfma_f32_16x16x32_bf16 v[54:57], v[174:177], v[190:193], v[54:57]
	v_mfma_f32_16x16x32_bf16 v[50:53], v[182:185], v[190:193], v[50:53]
	v_mfma_f32_16x16x32_bf16 v[38:41], v[174:177], v[198:201], v[38:41]
	v_mfma_f32_16x16x32_bf16 v[34:37], v[182:185], v[198:201], v[34:37]
	v_mfma_f32_16x16x32_bf16 v[22:25], v[174:177], v[206:209], v[22:25]
	v_mfma_f32_16x16x32_bf16 v[18:21], v[182:185], v[206:209], v[18:21]
	v_mfma_f32_16x16x32_bf16 v[6:9], v[174:177], v[236:239], v[6:9]
	v_mfma_f32_16x16x32_bf16 v[2:5], v[182:185], v[236:239], v[2:5]
	s_barrier
	s_add_i32 s56, 0, 0x18000
	s_add_i32 s57, 0, 0x1c000
	ds_read_b128 v[142:145], v147 offset:32768
	ds_read_b128 v[158:161], v147 offset:33792
	ds_read_b128 v[162:165], v147 offset:34816
	ds_read_b128 v[166:169], v147 offset:35840
	ds_read_b128 v[170:173], v147 offset:49152
	ds_read_b128 v[174:177], v147 offset:50176
	ds_read_b128 v[178:181], v147 offset:51200
	ds_read_b128 v[182:185], v147 offset:52224
	s_add_u32 s34, s34, 0x40000
	s_addc_u32 s35, s35, 0
	s_mov_b32 m0, s43
	ds_read_b128 v[186:189], v157 offset:32768
	ds_read_b128 v[190:193], v157 offset:33792
	ds_read_b128 v[194:197], v157 offset:34816
	ds_read_b128 v[198:201], v157 offset:35840
	ds_read_b128 v[202:205], v157 offset:36864
	ds_read_b128 v[206:209], v157 offset:37888
	ds_read_b128 v[220:223], v157 offset:38912
	ds_read_b128 v[236:239], v157 offset:39936
	global_load_lds_dwordx4 v130, s[34:35]
	s_mov_b32 m0, s46
	s_nop 0
	global_load_lds_dwordx4 v134, s[34:35]
	s_branch .Lpadj_2
	s_nop 0
	s_nop 0
	s_nop 0
	s_nop 0
	s_nop 0
	s_nop 0
	s_nop 0
	s_nop 0
	s_nop 0
	s_nop 0
	s_nop 0
	s_nop 0
	s_nop 0

.LBB0_362:
	s_ashr_i32 s23, s22, 31
	s_lshl_b64 s[24:25], s[22:23], 19
	s_add_u32 s24, s80, s24
	s_addc_u32 s25, s81, s25
	s_and_b64 s[26:27], s[6:7], exec
	s_cselect_b32 s23, s25, s35
	s_cselect_b32 s39, s24, s34
	s_ashr_i32 s21, s20, 31
	s_lshl_b64 s[26:27], s[20:21], 19
	s_add_u32 s26, s45, s26
	s_addc_u32 s27, s46, s27
	s_and_b64 s[36:37], s[6:7], exec
	s_cselect_b32 s21, s27, s31
	s_cselect_b32 s40, s26, s30
	s_add_u32 s41, s30, 0x100
	s_addc_u32 s43, s31, 0
	s_add_u32 s30, s34, 0x40080
	s_addc_u32 s31, s35, 0
	s_mov_b32 s56, -2
	s_add_u32 s34, s30, 0xfffc0080
	s_addc_u32 s35, s31, -1
	s_add_i32 s57, 0, 0x10000
	s_cmp_eq_u32 s56, 12
	s_cselect_b32 s37, s23, s35
	s_cselect_b32 s36, s39, s34
	s_cselect_b32 s35, s21, s43
	s_cselect_b32 s34, s40, s41
	s_add_i32 s60, 0, 0x14000
	ds_read_b128 v[142:145], v155
	ds_read_b128 v[168:171], v155 offset:1024
	ds_read_b128 v[172:175], v155 offset:2048
	ds_read_b128 v[176:179], v155 offset:3072
	ds_read_b128 v[180:183], v155 offset:16384
	ds_read_b128 v[184:187], v155 offset:17408
	ds_read_b128 v[188:191], v155 offset:18432
	ds_read_b128 v[192:195], v155 offset:19456
	s_add_i32 m0, s48, 0xc000
	ds_read_b128 v[196:199], v157
	ds_read_b128 v[200:203], v157 offset:1024
	ds_read_b128 v[204:207], v157 offset:2048
	ds_read_b128 v[220:223], v157 offset:3072
	ds_read_b128 v[236:239], v157 offset:4096
	ds_read_b128 v[240:243], v157 offset:5120
	ds_read_b128 v[244:247], v157 offset:6144
	ds_read_b128 v[248:251], v157 offset:7168
	global_load_lds_dwordx4 v140, s[30:31]
	s_add_i32 m0, s48, 0xe000
	s_nop 0
	global_load_lds_dwordx4 v138, s[30:31]
	s_branch .Lpadj_8
	s_nop 0
	s_nop 0
	s_nop 0
	s_nop 0
	s_nop 0
	s_nop 0
	s_nop 0
	s_nop 0
	s_nop 0
	s_nop 0

.Lpadj_9:
	s_waitcnt vmcnt(8)
	s_waitcnt lgkmcnt(0)
	s_barrier
	v_mfma_f32_16x16x32_bf16 v[62:65], v[142:145], v[196:199], 0
	v_mfma_f32_16x16x32_bf16 v[54:57], v[172:175], v[196:199], 0
	v_mfma_f32_16x16x32_bf16 v[46:49], v[142:145], v[204:207], 0
	v_mfma_f32_16x16x32_bf16 v[38:41], v[172:175], v[204:207], 0
	v_mfma_f32_16x16x32_bf16 v[30:33], v[142:145], v[236:239], 0
	v_mfma_f32_16x16x32_bf16 v[22:25], v[172:175], v[236:239], 0
	v_mfma_f32_16x16x32_bf16 v[14:17], v[142:145], v[244:247], 0
	v_mfma_f32_16x16x32_bf16 v[6:9], v[172:175], v[244:247], 0
	v_mfma_f32_16x16x32_bf16 v[62:65], v[168:171], v[200:203], v[62:65]
	v_mfma_f32_16x16x32_bf16 v[54:57], v[176:179], v[200:203], v[54:57]
	v_mfma_f32_16x16x32_bf16 v[46:49], v[168:171], v[220:223], v[46:49]
	v_mfma_f32_16x16x32_bf16 v[38:41], v[176:179], v[220:223], v[38:41]
	v_mfma_f32_16x16x32_bf16 v[30:33], v[168:171], v[240:243], v[30:33]
	v_mfma_f32_16x16x32_bf16 v[22:25], v[176:179], v[240:243], v[22:25]
	v_mfma_f32_16x16x32_bf16 v[14:17], v[168:171], v[248:251], v[14:17]
	v_mfma_f32_16x16x32_bf16 v[6:9], v[176:179], v[248:251], v[6:9]
	v_mfma_f32_16x16x32_bf16 v[58:61], v[180:183], v[196:199], 0
	v_mfma_f32_16x16x32_bf16 v[50:53], v[188:191], v[196:199], 0
	v_mfma_f32_16x16x32_bf16 v[42:45], v[180:183], v[204:207], 0
	v_mfma_f32_16x16x32_bf16 v[34:37], v[188:191], v[204:207], 0
	v_mfma_f32_16x16x32_bf16 v[26:29], v[180:183], v[236:239], 0
	v_mfma_f32_16x16x32_bf16 v[18:21], v[188:191], v[236:239], 0
	v_mfma_f32_16x16x32_bf16 v[10:13], v[180:183], v[244:247], 0
	v_mfma_f32_16x16x32_bf16 v[2:5], v[188:191], v[244:247], 0
	v_mfma_f32_16x16x32_bf16 v[58:61], v[184:187], v[200:203], v[58:61]
	v_mfma_f32_16x16x32_bf16 v[50:53], v[192:195], v[200:203], v[50:53]
	v_mfma_f32_16x16x32_bf16 v[42:45], v[184:187], v[220:223], v[42:45]
	v_mfma_f32_16x16x32_bf16 v[34:37], v[192:195], v[220:223], v[34:37]
	v_mfma_f32_16x16x32_bf16 v[26:29], v[184:187], v[240:243], v[26:29]
	v_mfma_f32_16x16x32_bf16 v[18:21], v[192:195], v[240:243], v[18:21]
	v_mfma_f32_16x16x32_bf16 v[10:13], v[184:187], v[248:251], v[10:13]
	v_mfma_f32_16x16x32_bf16 v[2:5], v[192:195], v[248:251], v[2:5]
	s_barrier
	s_add_i32 s57, 0, 0x18000
	s_add_i32 s58, 0, 0x1c000
	ds_read_b128 v[142:145], v155 offset:32768
	ds_read_b128 v[168:171], v155 offset:33792
	ds_read_b128 v[172:175], v155 offset:34816
	ds_read_b128 v[176:179], v155 offset:35840
	ds_read_b128 v[180:183], v155 offset:49152
	ds_read_b128 v[184:187], v155 offset:50176
	ds_read_b128 v[188:191], v155 offset:51200
	ds_read_b128 v[192:195], v155 offset:52224
	s_add_u32 s36, s36, 0x40000
	s_addc_u32 s37, s37, 0
	s_mov_b32 m0, s50
	ds_read_b128 v[196:199], v157 offset:32768
	ds_read_b128 v[200:203], v157 offset:33792
	ds_read_b128 v[204:207], v157 offset:34816
	ds_read_b128 v[220:223], v157 offset:35840
	ds_read_b128 v[236:239], v157 offset:36864
	ds_read_b128 v[240:243], v157 offset:37888
	ds_read_b128 v[244:247], v157 offset:38912
	ds_read_b128 v[248:251], v157 offset:39936
	global_load_lds_dwordx4 v136, s[36:37]
	s_mov_b32 m0, s51
	s_nop 0
	global_load_lds_dwordx4 v132, s[36:37]
	s_branch .Lpadj_10
	s_nop 0
	s_nop 0
	s_nop 0
	s_nop 0
	s_nop 0
	s_nop 0
	s_nop 0
	s_nop 0
	s_nop 0
	s_nop 0
	s_nop 0
	s_nop 0
	s_nop 0

.LBB0_476:
	s_add_i32 s63, s31, 2
	s_add_u32 s38, s28, s36
	s_addc_u32 s39, s29, s37
	s_add_u32 s64, s26, s36
	s_addc_u32 s65, s27, s37
	s_add_i32 s66, 0, 0x10000
	s_cmp_eq_u32 s59, s31
	s_cselect_b32 s39, s9, s39
	s_cselect_b32 s38, s8, s38
	s_cselect_b32 s65, s35, s65
	s_cselect_b32 s64, s34, s64
	s_add_i32 s31, 0, 0x14000
	ds_read_b128 v[148:151], v146
	ds_read_b128 v[152:155], v146 offset:1024
	ds_read_b128 v[156:159], v146 offset:2048
	ds_read_b128 v[160:163], v146 offset:3072
	ds_read_b128 v[164:167], v146 offset:16384
	ds_read_b128 v[168:171], v146 offset:17408
	ds_read_b128 v[172:175], v146 offset:18432
	ds_read_b128 v[176:179], v146 offset:19456
	s_add_i32 m0, s51, 0xc000
	ds_read_b128 v[180:183], v147
	ds_read_b128 v[184:187], v147 offset:1024
	ds_read_b128 v[188:191], v147 offset:2048
	ds_read_b128 v[192:195], v147 offset:3072
	ds_read_b128 v[196:199], v147 offset:4096
	ds_read_b128 v[200:203], v147 offset:5120
	ds_read_b128 v[204:207], v147 offset:6144
	ds_read_b128 v[220:223], v147 offset:7168
	global_load_lds_dwordx4 v142, s[28:29]
	s_add_i32 m0, s51, 0xe000
	s_nop 0
	global_load_lds_dwordx4 v144, s[28:29]
	s_branch .Lpadj_16
	s_nop 0
	s_nop 0
	s_nop 0
	s_nop 0
	s_nop 0
	s_nop 0
	s_nop 0
	s_nop 0
	s_nop 0
	s_nop 0
	s_nop 0
	s_nop 0
	s_nop 0
	s_nop 0

.Lpadj_19:
	s_waitcnt vmcnt(8)
	s_waitcnt lgkmcnt(0)
	s_barrier
	v_mfma_f32_16x16x32_bf16 v[62:65], v[148:151], v[180:183], v[62:65]
	v_mfma_f32_16x16x32_bf16 v[58:61], v[156:159], v[180:183], v[58:61]
	v_mfma_f32_16x16x32_bf16 v[46:49], v[148:151], v[188:191], v[46:49]
	v_mfma_f32_16x16x32_bf16 v[42:45], v[156:159], v[188:191], v[42:45]
	v_mfma_f32_16x16x32_bf16 v[30:33], v[148:151], v[196:199], v[30:33]
	v_mfma_f32_16x16x32_bf16 v[26:29], v[156:159], v[196:199], v[26:29]
	v_mfma_f32_16x16x32_bf16 v[14:17], v[148:151], v[204:207], v[14:17]
	v_mfma_f32_16x16x32_bf16 v[10:13], v[156:159], v[204:207], v[10:13]
	v_mfma_f32_16x16x32_bf16 v[62:65], v[152:155], v[184:187], v[62:65]
	v_mfma_f32_16x16x32_bf16 v[58:61], v[160:163], v[184:187], v[58:61]
	v_mfma_f32_16x16x32_bf16 v[46:49], v[152:155], v[192:195], v[46:49]
	v_mfma_f32_16x16x32_bf16 v[42:45], v[160:163], v[192:195], v[42:45]
	v_mfma_f32_16x16x32_bf16 v[30:33], v[152:155], v[200:203], v[30:33]
	v_mfma_f32_16x16x32_bf16 v[26:29], v[160:163], v[200:203], v[26:29]
	v_mfma_f32_16x16x32_bf16 v[14:17], v[152:155], v[220:223], v[14:17]
	v_mfma_f32_16x16x32_bf16 v[10:13], v[160:163], v[220:223], v[10:13]
	v_mfma_f32_16x16x32_bf16 v[54:57], v[164:167], v[180:183], v[54:57]
	v_mfma_f32_16x16x32_bf16 v[50:53], v[172:175], v[180:183], v[50:53]
	v_mfma_f32_16x16x32_bf16 v[38:41], v[164:167], v[188:191], v[38:41]
	v_mfma_f32_16x16x32_bf16 v[34:37], v[172:175], v[188:191], v[34:37]
	v_mfma_f32_16x16x32_bf16 v[22:25], v[164:167], v[196:199], v[22:25]
	v_mfma_f32_16x16x32_bf16 v[18:21], v[172:175], v[196:199], v[18:21]
	v_mfma_f32_16x16x32_bf16 v[6:9], v[164:167], v[204:207], v[6:9]
	v_mfma_f32_16x16x32_bf16 v[2:5], v[172:175], v[204:207], v[2:5]
	v_mfma_f32_16x16x32_bf16 v[54:57], v[168:171], v[184:187], v[54:57]
	v_mfma_f32_16x16x32_bf16 v[50:53], v[176:179], v[184:187], v[50:53]
	v_mfma_f32_16x16x32_bf16 v[38:41], v[168:171], v[192:195], v[38:41]
	v_mfma_f32_16x16x32_bf16 v[34:37], v[176:179], v[192:195], v[34:37]
	v_mfma_f32_16x16x32_bf16 v[22:25], v[168:171], v[200:203], v[22:25]
	v_mfma_f32_16x16x32_bf16 v[18:21], v[176:179], v[200:203], v[18:21]
	v_mfma_f32_16x16x32_bf16 v[6:9], v[168:171], v[220:223], v[6:9]
	v_mfma_f32_16x16x32_bf16 v[2:5], v[176:179], v[220:223], v[2:5]
	s_barrier
	s_add_u32 s36, s36, 0x100
	s_addc_u32 s37, s37, 0
	v_add_u32_e32 v144, 0x100, v144
	v_add_u32_e32 v142, 0x100, v142
	s_cmp_ge_u32 s63, s56
	s_mov_b32 s31, s63
	s_cbranch_scc0 .LBB0_476
	s_and_b64 vcc, exec, s[6:7]
	s_cbranch_vccnz .LBB0_464
	v_mov_b32_e32 v2, 0
	s_mov_b32 s55, s61
	s_mov_b32 s50, s62
	s_mov_b64 s[26:27], s[34:35]
	s_mov_b64 s[28:29], s[8:9]
	s_mov_b32 s60, s30
	v_mov_b32_e32 v3, v2
	v_mov_b32_e32 v4, v2
	v_mov_b32_e32 v5, v2
	v_mov_b32_e32 v6, v2
	v_mov_b32_e32 v7, v2
	v_mov_b32_e32 v8, v2
	v_mov_b32_e32 v9, v2
	v_mov_b32_e32 v18, v2
	v_mov_b32_e32 v19, v2
	v_mov_b32_e32 v20, v2
	v_mov_b32_e32 v21, v2
	v_mov_b32_e32 v22, v2
	v_mov_b32_e32 v23, v2
	v_mov_b32_e32 v24, v2
	v_mov_b32_e32 v25, v2
	v_mov_b32_e32 v34, v2
	v_mov_b32_e32 v35, v2
	v_mov_b32_e32 v36, v2
	v_mov_b32_e32 v37, v2
	v_mov_b32_e32 v38, v2
	v_mov_b32_e32 v39, v2
	v_mov_b32_e32 v40, v2
	v_mov_b32_e32 v41, v2
	v_mov_b32_e32 v50, v2
	v_mov_b32_e32 v51, v2
	v_mov_b32_e32 v52, v2
	v_mov_b32_e32 v53, v2
	v_mov_b32_e32 v54, v2
	v_mov_b32_e32 v55, v2
	v_mov_b32_e32 v56, v2
	v_mov_b32_e32 v57, v2
	v_mov_b32_e32 v10, v2
	v_mov_b32_e32 v11, v2
	v_mov_b32_e32 v12, v2
	v_mov_b32_e32 v13, v2
	v_mov_b32_e32 v14, v2
	v_mov_b32_e32 v15, v2
	v_mov_b32_e32 v16, v2
	v_mov_b32_e32 v17, v2
	v_mov_b32_e32 v26, v2
	v_mov_b32_e32 v27, v2
	v_mov_b32_e32 v28, v2
	v_mov_b32_e32 v29, v2
	v_mov_b32_e32 v30, v2
	v_mov_b32_e32 v31, v2
	v_mov_b32_e32 v32, v2
	v_mov_b32_e32 v33, v2
	v_mov_b32_e32 v42, v2
	v_mov_b32_e32 v43, v2
	v_mov_b32_e32 v44, v2
	v_mov_b32_e32 v45, v2
	v_mov_b32_e32 v46, v2
	v_mov_b32_e32 v47, v2
	v_mov_b32_e32 v48, v2
	v_mov_b32_e32 v49, v2
	v_mov_b32_e32 v58, v2
	v_mov_b32_e32 v59, v2
	v_mov_b32_e32 v60, v2
	v_mov_b32_e32 v61, v2
	v_mov_b32_e32 v62, v2
	v_mov_b32_e32 v63, v2
	v_mov_b32_e32 v64, v2
	v_mov_b32_e32 v65, v2
	v_mov_b32_e32 v66, v2
	v_mov_b32_e32 v67, v2
	v_mov_b32_e32 v68, v2
	v_mov_b32_e32 v69, v2
	v_mov_b32_e32 v70, v2
	v_mov_b32_e32 v71, v2
	v_mov_b32_e32 v72, v2
	v_mov_b32_e32 v73, v2
	v_mov_b32_e32 v82, v2
	v_mov_b32_e32 v83, v2
	v_mov_b32_e32 v84, v2
	v_mov_b32_e32 v85, v2
	v_mov_b32_e32 v86, v2
	v_mov_b32_e32 v87, v2
	v_mov_b32_e32 v88, v2
	v_mov_b32_e32 v89, v2
	v_mov_b32_e32 v98, v2
	v_mov_b32_e32 v99, v2
	v_mov_b32_e32 v100, v2
	v_mov_b32_e32 v101, v2
	v_mov_b32_e32 v102, v2
	v_mov_b32_e32 v103, v2
	v_mov_b32_e32 v104, v2
	v_mov_b32_e32 v105, v2
	v_mov_b32_e32 v114, v2
	v_mov_b32_e32 v115, v2
	v_mov_b32_e32 v116, v2
	v_mov_b32_e32 v117, v2
	v_mov_b32_e32 v118, v2
	v_mov_b32_e32 v119, v2
	v_mov_b32_e32 v120, v2
	v_mov_b32_e32 v121, v2
	v_mov_b32_e32 v74, v2
	v_mov_b32_e32 v75, v2
	v_mov_b32_e32 v76, v2
	v_mov_b32_e32 v77, v2
	v_mov_b32_e32 v78, v2
	v_mov_b32_e32 v79, v2
	v_mov_b32_e32 v80, v2
	v_mov_b32_e32 v81, v2
	v_mov_b32_e32 v90, v2
	v_mov_b32_e32 v91, v2
	v_mov_b32_e32 v92, v2
	v_mov_b32_e32 v93, v2
	v_mov_b32_e32 v94, v2
	v_mov_b32_e32 v95, v2
	v_mov_b32_e32 v96, v2
	v_mov_b32_e32 v97, v2
	v_mov_b32_e32 v106, v2
	v_mov_b32_e32 v107, v2
	v_mov_b32_e32 v108, v2
	v_mov_b32_e32 v109, v2
	v_mov_b32_e32 v110, v2
	v_mov_b32_e32 v111, v2
	v_mov_b32_e32 v112, v2
	v_mov_b32_e32 v113, v2
	v_mov_b32_e32 v122, v2
	v_mov_b32_e32 v123, v2
	v_mov_b32_e32 v124, v2
	v_mov_b32_e32 v125, v2
	v_mov_b32_e32 v126, v2
	v_mov_b32_e32 v127, v2
	v_mov_b32_e32 v128, v2
	v_mov_b32_e32 v129, v2
	s_branch .LBB0_464

.LBB0_639:
	s_ashr_i32 s13, s12, 31
	s_lshl_b64 s[14:15], s[12:13], 19
	s_add_u32 s14, s80, s14
	s_addc_u32 s15, s81, s15
	s_and_b64 s[16:17], s[4:5], exec
	s_cselect_b32 s13, s15, s23
	s_cselect_b32 s19, s14, s22
	s_ashr_i32 s11, s10, 31
	s_lshl_b64 s[16:17], s[10:11], 19
	s_add_u32 s16, s26, s16
	s_addc_u32 s17, s27, s17
	s_and_b64 s[24:25], s[4:5], exec
	s_cselect_b32 s11, s17, s21
	s_cselect_b32 s41, s16, s20
	s_add_u32 s43, s20, 0x100
	s_addc_u32 s44, s21, 0
	s_add_u32 s20, s22, 0x40080
	s_addc_u32 s21, s23, 0
	s_mov_b32 s45, -2
	s_add_u32 s22, s20, 0xfffc0080
	s_addc_u32 s23, s21, -1
	s_add_i32 s46, 0, 0x10000
	s_cmp_eq_u32 s45, 12
	s_cselect_b32 s25, s13, s23
	s_cselect_b32 s24, s19, s22
	s_cselect_b32 s23, s11, s44
	s_cselect_b32 s22, s41, s43
	s_add_i32 s48, 0, 0x14000
	ds_read_b128 v[164:167], v159
	ds_read_b128 v[168:171], v159 offset:1024
	ds_read_b128 v[172:175], v159 offset:2048
	ds_read_b128 v[176:179], v159 offset:3072
	ds_read_b128 v[180:183], v159 offset:16384
	ds_read_b128 v[184:187], v159 offset:17408
	ds_read_b128 v[188:191], v159 offset:18432
	ds_read_b128 v[192:195], v159 offset:19456
	s_add_i32 m0, s30, 0xc000
	ds_read_b128 v[196:199], v162
	ds_read_b128 v[200:203], v162 offset:1024
	ds_read_b128 v[204:207], v162 offset:2048
	ds_read_b128 v[220:223], v162 offset:3072
	ds_read_b128 v[236:239], v162 offset:4096
	ds_read_b128 v[240:243], v162 offset:5120
	ds_read_b128 v[244:247], v162 offset:6144
	ds_read_b128 v[248:251], v162 offset:7168
	global_load_lds_dwordx4 v140, s[20:21]
	s_add_i32 m0, s30, 0xe000
	s_nop 0
	global_load_lds_dwordx4 v138, s[20:21]
	s_branch .Lpadj_20
	s_nop 0
	s_nop 0
	s_nop 0
	s_nop 0
	s_nop 0
	s_nop 0
	s_nop 0
	s_nop 0
	s_nop 0
	s_nop 0
	s_nop 0
	s_nop 0

.Lpadj_21:
	s_waitcnt vmcnt(8)
	s_waitcnt lgkmcnt(0)
	s_barrier
	v_mfma_f32_16x16x32_bf16 v[62:65], v[164:167], v[196:199], 0
	v_mfma_f32_16x16x32_bf16 v[58:61], v[172:175], v[196:199], 0
	v_mfma_f32_16x16x32_bf16 v[54:57], v[164:167], v[204:207], 0
	v_mfma_f32_16x16x32_bf16 v[50:53], v[172:175], v[204:207], 0
	v_mfma_f32_16x16x32_bf16 v[46:49], v[164:167], v[236:239], 0
	v_mfma_f32_16x16x32_bf16 v[42:45], v[172:175], v[236:239], 0
	v_mfma_f32_16x16x32_bf16 v[38:41], v[164:167], v[244:247], 0
	v_mfma_f32_16x16x32_bf16 v[34:37], v[172:175], v[244:247], 0
	v_mfma_f32_16x16x32_bf16 v[62:65], v[168:171], v[200:203], v[62:65]
	v_mfma_f32_16x16x32_bf16 v[58:61], v[176:179], v[200:203], v[58:61]
	v_mfma_f32_16x16x32_bf16 v[54:57], v[168:171], v[220:223], v[54:57]
	v_mfma_f32_16x16x32_bf16 v[50:53], v[176:179], v[220:223], v[50:53]
	v_mfma_f32_16x16x32_bf16 v[46:49], v[168:171], v[240:243], v[46:49]
	v_mfma_f32_16x16x32_bf16 v[42:45], v[176:179], v[240:243], v[42:45]
	v_mfma_f32_16x16x32_bf16 v[38:41], v[168:171], v[248:251], v[38:41]
	v_mfma_f32_16x16x32_bf16 v[34:37], v[176:179], v[248:251], v[34:37]
	v_mfma_f32_16x16x32_bf16 v[30:33], v[180:183], v[196:199], 0
	v_mfma_f32_16x16x32_bf16 v[26:29], v[188:191], v[196:199], 0
	v_mfma_f32_16x16x32_bf16 v[22:25], v[180:183], v[204:207], 0
	v_mfma_f32_16x16x32_bf16 v[18:21], v[188:191], v[204:207], 0
	v_mfma_f32_16x16x32_bf16 v[14:17], v[180:183], v[236:239], 0
	v_mfma_f32_16x16x32_bf16 v[10:13], v[188:191], v[236:239], 0
	v_mfma_f32_16x16x32_bf16 v[6:9], v[180:183], v[244:247], 0
	v_mfma_f32_16x16x32_bf16 v[2:5], v[188:191], v[244:247], 0
	v_mfma_f32_16x16x32_bf16 v[30:33], v[184:187], v[200:203], v[30:33]
	v_mfma_f32_16x16x32_bf16 v[26:29], v[192:195], v[200:203], v[26:29]
	v_mfma_f32_16x16x32_bf16 v[22:25], v[184:187], v[220:223], v[22:25]
	v_mfma_f32_16x16x32_bf16 v[18:21], v[192:195], v[220:223], v[18:21]
	v_mfma_f32_16x16x32_bf16 v[14:17], v[184:187], v[240:243], v[14:17]
	v_mfma_f32_16x16x32_bf16 v[10:13], v[192:195], v[240:243], v[10:13]
	v_mfma_f32_16x16x32_bf16 v[6:9], v[184:187], v[248:251], v[6:9]
	v_mfma_f32_16x16x32_bf16 v[2:5], v[192:195], v[248:251], v[2:5]
	s_barrier
	s_add_i32 s46, 0, 0x18000
	s_add_i32 s47, 0, 0x1c000
	ds_read_b128 v[164:167], v159 offset:32768
	ds_read_b128 v[168:171], v159 offset:33792
	ds_read_b128 v[172:175], v159 offset:34816
	ds_read_b128 v[176:179], v159 offset:35840
	ds_read_b128 v[180:183], v159 offset:49152
	ds_read_b128 v[184:187], v159 offset:50176
	ds_read_b128 v[188:191], v159 offset:51200
	ds_read_b128 v[192:195], v159 offset:52224
	s_add_u32 s24, s24, 0x40000
	s_addc_u32 s25, s25, 0
	s_mov_b32 m0, s34
	ds_read_b128 v[196:199], v162 offset:32768
	ds_read_b128 v[200:203], v162 offset:33792
	ds_read_b128 v[204:207], v162 offset:34816
	ds_read_b128 v[220:223], v162 offset:35840
	ds_read_b128 v[236:239], v162 offset:36864
	ds_read_b128 v[240:243], v162 offset:37888
	ds_read_b128 v[244:247], v162 offset:38912
	ds_read_b128 v[248:251], v162 offset:39936
	global_load_lds_dwordx4 v136, s[24:25]
	s_mov_b32 m0, s35
	s_nop 0
	global_load_lds_dwordx4 v132, s[24:25]
	s_branch .Lpadj_22
	s_nop 0
	s_nop 0
	s_nop 0
	s_nop 0
	s_nop 0
	s_nop 0
	s_nop 0
	s_nop 0
	s_nop 0
	s_nop 0
	s_nop 0
	s_nop 0
	s_nop 0
